# speedup vs baseline: 1.0098x; 1.0098x over previous
; #define LAS __attribute__((address_space(3)))
; __global__ void __launch_bounds__(512, 2) mega_fwd(Params p, int ph_lo, int ph_hi) {
;     extern __shared__ __attribute__((aligned(16))) unsigned char lds[];
;     cg::grid_group grid = cg::this_grid();
;     volatile LAS unsigned* xst = (volatile LAS unsigned*)((LAS unsigned char*)lds + 131072);
;     if (threadIdx.x == 0) { xst[0] = 0u; xst[1] = 0u; }
;     __syncthreads();
;     const XcdBarrier xbar = xcd_barrier_post((unsigned*)(p.ws + WS_CTRL + 4096), xst);
_Z8mega_fwd6Paramsii:
	v_readfirstlane_b32 s99, v0
	s_mov_b64 s[72:73], s[0:1]
	s_load_dwordx8 s[88:95], s[0:1], 0x100
	s_nop 0
	s_load_dword s0, s[0:1], 0x140
	s_nop 0
	s_load_dwordx4 s[76:79], s[72:73], 0x120
	s_load_dwordx2 s[82:83], s[72:73], 0x138
	v_cmp_eq_u32_e64 s[74:75], 0, v0
	s_waitcnt lgkmcnt(0)
	v_writelane_b32 v244, s0, 0
	s_and_saveexec_b64 s[4:5], s[74:75]
	s_cbranch_execz .LBB0_2
	s_add_i32 s0, 0, 0x20000
	v_mov_b32_e32 v1, 0
	v_mov_b32_e32 v2, s0
	s_add_i32 s0, 0, 0x20004
	ds_write_b32 v2, v1
	v_mov_b32_e32 v2, s0
	ds_write_b32 v2, v1

; #define PG8_WAIT_V(n) asm volatile("s_waitcnt vmcnt(" #n ")" ::: "memory")
; #define PG8_BAR __builtin_amdgcn_s_barrier()
; template <class Epi, class Sched, bool ALIGN_EPI = false, bool SP2 = false>
; __device__ __forceinline__ void gemm_phase(PG8_LAS unsigned char* lds, const Gemm g, const Sched& S, const Epi& E) {
;     ...
;     PG8_WAIT_V(0);
;     if constexpr (!ALIGN_EPI) { if (wr == 0) PG8_BAR; }
;     PG8_BAR;
.LBB0_192:
	s_setprio 0
	s_waitcnt vmcnt(0) lgkmcnt(0)
	s_barrier

; #define PG8_STAGE(bufoff, gbase, voff) do { _Pragma("unroll") for (int _i = 0; _i < 2; ++_i) \
;         __builtin_amdgcn_global_load_lds((const unsigned*)((const char*)(gbase) + (voff)[_i]), (PG8_LAS unsigned*)(lds + (bufoff) + ldsw + _i * 8192), 16, 0, 0); } while (0)
; #define PG8_WAIT_V(n) asm volatile("s_waitcnt vmcnt(" #n ")" ::: "memory")
; #define PG8_BAR __builtin_amdgcn_s_barrier()
; template <class Epi, class Sched, bool ALIGN_EPI = false, bool SP2 = false>
; __device__ __forceinline__ void gemm_phase(PG8_LAS unsigned char* lds, const Gemm g, const Sched& S, const Epi& E) {
;     const int tid = threadIdx.x, wid = __builtin_amdgcn_readfirstlane(tid >> 6), lane = tid & 63, wr = wid >> 2, wc = wid & 3, fr = lane & 15, fq = lane >> 4;
;     const int K = g.K, nt = K / BK;
;     unsigned voffA[2], voffB[2];
; #pragma unroll
;     for (int i = 0; i < 2; ++i) { int R, C; stage_rc(tid * 16 + i * 8192, R, C); const int Rb = Epi::PERM ? ((R & ~31) + perm32(R & 31)) : R;
;         voffA[i] = (unsigned)(R * K + C) * 2u; voffB[i] = (unsigned)(Rb * K + C) * 2u; }
;     const size_t kstep = (size_t)(BK * 2);
;     const size_t hstep = (size_t)HALF * K * 2;
;     const size_t tstep = 2 * hstep;
;     const unsigned ldsw = (unsigned)wid * 1024u;
;     const int aoff = lds_byte(wr * 64 + fr, fq * 8), boff = lds_byte(wc * 32 + fr, fq * 8);
;     ...
;         PG8_WAIT_V(2); PG8_BAR;
;         PG8_STAGE(PG8_SB(1, 0), cB + kstep, voffB); PG8_STAGE(PG8_SA(1, 0), cA + kstep, voffA); PG8_STAGE(PG8_SB(1, 1), cB + hstep + kstep, voffB);
;         PG8_WAIT_V(6); PG8_BAR;
.LBB0_567:
	s_add_u32 s16, s6, 0x17500000
	s_mov_b64 s[18:19], 0x80
	s_addc_u32 s17, s7, 0
	s_add_i32 m0, s0, 0x18000
	v_lshl_add_u64 v[10:11], v[10:11], 0, s[18:19]
	s_waitcnt vmcnt(2)
	s_barrier
	global_load_lds_dwordx4 v[10:11], off
	v_lshl_add_u64 v[6:7], v[6:7], 0, s[18:19]
	s_add_i32 m0, s0, 0x1a000
	s_add_i32 s42, s0, 0x8000
	global_load_lds_dwordx4 v[6:7], off
	v_lshl_add_u64 v[6:7], v[8:9], 0, s[18:19]
	s_mov_b32 m0, s42
	s_add_i32 s43, s0, 0xa000
	global_load_lds_dwordx4 v[6:7], off
	v_lshl_add_u64 v[6:7], v[12:13], 0, s[18:19]
	s_mov_b32 m0, s43
	v_lshl_add_u64 v[4:5], v[4:5], 0, s[18:19]
	global_load_lds_dwordx4 v[6:7], off
	s_add_i32 m0, s0, 0x1c000
	v_lshl_add_u64 v[2:3], v[2:3], 0, s[18:19]
	global_load_lds_dwordx4 v[4:5], off
	s_add_i32 m0, s0, 0x1e000
	s_lshr_b32 s5, s5, 26
	global_load_lds_dwordx4 v[2:3], off
	v_and_b32_e32 v2, 15, v0
	s_add_i32 s5, s4, s5
	v_lshlrev_b32_e32 v3, 1, v18
	v_lshlrev_b32_e32 v4, 2, v0
	s_ashr_i32 s44, s5, 6
	v_lshl_or_b32 v1, s23, 6, v2
	v_lshl_or_b32 v2, v2, 6, v3
	s_lshl_b32 s5, s23, 13
	v_and_b32_e32 v4, 32, v4
	v_bitop3_b32 v5, v2, s5, v4 bitop3:0xde
	s_lshl_b32 s5, s21, 5
	s_and_b32 s5, s5, 0x60
	v_lshlrev_b32_e32 v2, 6, v0
	s_movk_i32 s6, 0x3c0
	v_and_or_b32 v2, v2, s6, v3
	s_lshl_b32 s6, s5, 7
	v_bitop3_b32 v146, s6, v2, v4 bitop3:0xf6
	v_add_u32_e32 v2, v19, v16
	v_mul_lo_u32 v2, s4, v2
	v_lshlrev_b32_e32 v2, 1, v2
	v_add3_u32 v2, v14, v2, v15
	v_mov_b32_e32 v3, v133
	s_cmp_gt_i32 s4, 63
	v_lshl_add_u64 v[138:139], s[10:11], 0, v[2:3]
	v_add_u32_e32 v2, v17, v16
	s_sext_i32_i8 s57, s20
	s_cselect_b64 s[20:21], -1, 0
	s_add_i32 s45, s44, -2
	v_mul_lo_u32 v2, s4, v2
	s_waitcnt vmcnt(6)
	s_cmpk_lt_u32 s22, 0x100
	v_lshlrev_b32_e32 v2, 1, v2
	s_cselect_b64 s[22:23], -1, 0
	v_add3_u32 v2, v14, v2, v15
	s_add_i32 s52, 0, 0x10000
	s_add_i32 s53, 0, 0x14000
	s_ashr_i32 s46, s82, 31
	s_mov_b32 s47, s82
	v_or_b32_e32 v147, s5, v18
	v_lshl_add_u64 v[140:141], s[10:11], 0, v[2:3]
	v_mov_b64_e32 v[142:143], 0x200
	v_mov_b64_e32 v[144:145], 0x1ff
	v_add_u32_e32 v148, s52, v146
	v_add_u32_e32 v149, s53, v146
	v_add_u32_e32 v150, 0, v5
	s_barrier
	s_waitcnt vmcnt(0)
	s_bitcmp1_b32 s99, 8
	s_cbranch_scc0 .Lprio_skip_0
	s_setprio 1
.Lprio_skip_0:
	s_branch .LBB0_570

; #define PG8_STAGE(bufoff, gbase, voff) do { _Pragma("unroll") for (int _i = 0; _i < 2; ++_i) \
;         __builtin_amdgcn_global_load_lds((const unsigned*)((const char*)(gbase) + (voff)[_i]), (PG8_LAS unsigned*)(lds + (bufoff) + ldsw + _i * 8192), 16, 0, 0); } while (0)
; #define PG8_WAIT_V(n) asm volatile("s_waitcnt vmcnt(" #n ")" ::: "memory")
; #define PG8_BAR __builtin_amdgcn_s_barrier()
; template <class Epi, class Sched, bool ALIGN_EPI = false, bool SP2 = false>
; __device__ __forceinline__ void gemm_phase(PG8_LAS unsigned char* lds, const Gemm g, const Sched& S, const Epi& E) {
;     const int tid = threadIdx.x, wid = __builtin_amdgcn_readfirstlane(tid >> 6), lane = tid & 63, wr = wid >> 2, wc = wid & 3, fr = lane & 15, fq = lane >> 4;
;     const int K = g.K, nt = K / BK;
;     unsigned voffA[2], voffB[2];
; #pragma unroll
;     for (int i = 0; i < 2; ++i) { int R, C; stage_rc(tid * 16 + i * 8192, R, C); const int Rb = Epi::PERM ? ((R & ~31) + perm32(R & 31)) : R;
;         voffA[i] = (unsigned)(R * K + C) * 2u; voffB[i] = (unsigned)(Rb * K + C) * 2u; }
;     const size_t kstep = (size_t)(BK * 2);
;     const size_t hstep = (size_t)HALF * K * 2;
;     const size_t tstep = 2 * hstep;
;     const unsigned ldsw = (unsigned)wid * 1024u;
;     const int aoff = lds_byte(wr * 64 + fr, fq * 8), boff = lds_byte(wc * 32 + fr, fq * 8);
;     ...
;         PG8_WAIT_V(2); PG8_BAR;
;         PG8_STAGE(PG8_SB(1, 0), cB + kstep, voffB); PG8_STAGE(PG8_SA(1, 0), cA + kstep, voffA); PG8_STAGE(PG8_SB(1, 1), cB + hstep + kstep, voffB);
;         PG8_WAIT_V(6); PG8_BAR;
.LBB0_738:
	s_add_u32 s16, s6, 0xc500000
	s_mov_b64 s[18:19], 0x80
	s_addc_u32 s17, s7, 0
	s_add_i32 m0, s40, 0x18000
	v_lshl_add_u64 v[10:11], v[10:11], 0, s[18:19]
	s_waitcnt vmcnt(2)
	s_barrier
	global_load_lds_dwordx4 v[10:11], off
	v_lshl_add_u64 v[6:7], v[6:7], 0, s[18:19]
	s_add_i32 m0, s40, 0x1a000
	s_add_i32 s45, s40, 0x8000
	global_load_lds_dwordx4 v[6:7], off
	v_lshl_add_u64 v[6:7], v[8:9], 0, s[18:19]
	s_mov_b32 m0, s45
	s_add_i32 s46, s40, 0xa000
	global_load_lds_dwordx4 v[6:7], off
	v_lshl_add_u64 v[6:7], v[12:13], 0, s[18:19]
	s_mov_b32 m0, s46
	v_lshl_add_u64 v[4:5], v[4:5], 0, s[18:19]
	global_load_lds_dwordx4 v[6:7], off
	s_add_i32 m0, s40, 0x1c000
	v_lshl_add_u64 v[2:3], v[2:3], 0, s[18:19]
	global_load_lds_dwordx4 v[4:5], off
	s_add_i32 m0, s40, 0x1e000
	s_lshr_b32 s5, s5, 26
	global_load_lds_dwordx4 v[2:3], off
	v_and_b32_e32 v2, 15, v0
	s_add_i32 s5, s4, s5
	v_lshlrev_b32_e32 v3, 1, v16
	v_lshlrev_b32_e32 v4, 2, v0
	s_ashr_i32 s47, s5, 6
	v_lshl_or_b32 v1, s23, 6, v2
	v_lshl_or_b32 v2, v2, 6, v3
	s_lshl_b32 s5, s23, 13
	v_and_b32_e32 v4, 32, v4
	v_bitop3_b32 v5, v2, s5, v4 bitop3:0xde
	s_lshl_b32 s5, s21, 5
	s_and_b32 s5, s5, 0x60
	v_lshlrev_b32_e32 v2, 6, v0
	s_movk_i32 s6, 0x3c0
	v_and_or_b32 v2, v2, s6, v3
	s_lshl_b32 s6, s5, 7
	v_bitop3_b32 v146, s6, v2, v4 bitop3:0xf6
	v_add_u32_e32 v2, v18, v17
	v_mul_lo_u32 v2, s4, v2
	v_lshlrev_b32_e32 v2, 1, v2
	v_add3_u32 v2, v14, v2, v15
	v_mov_b32_e32 v3, v135
	s_cmp_gt_i32 s4, 63
	v_lshl_add_u64 v[138:139], s[10:11], 0, v[2:3]
	v_add_u32_e32 v2, v19, v17
	s_sext_i32_i16 s1, s20
	s_cselect_b64 s[20:21], -1, 0
	s_add_i32 s48, s47, -2
	v_mul_lo_u32 v2, s4, v2
	s_waitcnt vmcnt(6)
	s_cmpk_lt_u32 s22, 0x100
	v_lshlrev_b32_e32 v2, 1, v2
	s_cselect_b64 s[22:23], -1, 0
	v_add3_u32 v2, v14, v2, v15
	s_add_i32 s53, 0, 0x10000
	s_add_i32 s54, 0, 0x14000
	s_ashr_i32 s49, s82, 31
	s_mov_b32 s52, s82
	v_or_b32_e32 v147, s5, v16
	v_lshl_add_u64 v[140:141], s[10:11], 0, v[2:3]
	v_mov_b64_e32 v[142:143], 0xb00
	v_mov_b64_e32 v[144:145], 0xaff
	v_add_u32_e32 v148, s53, v146
	v_add_u32_e32 v149, s54, v146
	v_add_u32_e32 v150, 0, v5
	s_movk_i32 s55, 0x2c00
	s_barrier
	s_waitcnt vmcnt(0)
	s_bitcmp1_b32 s99, 8
	s_cbranch_scc0 .Lprio_skip_1
	s_setprio 1

; #define PG8_STAGE(bufoff, gbase, voff) do { _Pragma("unroll") for (int _i = 0; _i < 2; ++_i) \
;         __builtin_amdgcn_global_load_lds((const unsigned*)((const char*)(gbase) + (voff)[_i]), (PG8_LAS unsigned*)(lds + (bufoff) + ldsw + _i * 8192), 16, 0, 0); } while (0)
; #define PG8_WAIT_V(n) asm volatile("s_waitcnt vmcnt(" #n ")" ::: "memory")
; #define PG8_BAR __builtin_amdgcn_s_barrier()
; template <class Epi, class Sched, bool ALIGN_EPI = false, bool SP2 = false>
; __device__ __forceinline__ void gemm_phase(PG8_LAS unsigned char* lds, const Gemm g, const Sched& S, const Epi& E) {
;     const int tid = threadIdx.x, wid = __builtin_amdgcn_readfirstlane(tid >> 6), lane = tid & 63, wr = wid >> 2, wc = wid & 3, fr = lane & 15, fq = lane >> 4;
;     const int K = g.K, nt = K / BK;
;     unsigned voffA[2], voffB[2];
; #pragma unroll
;     for (int i = 0; i < 2; ++i) { int R, C; stage_rc(tid * 16 + i * 8192, R, C); const int Rb = Epi::PERM ? ((R & ~31) + perm32(R & 31)) : R;
;         voffA[i] = (unsigned)(R * K + C) * 2u; voffB[i] = (unsigned)(Rb * K + C) * 2u; }
;     const size_t kstep = (size_t)(BK * 2);
;     const size_t hstep = (size_t)HALF * K * 2;
;     const size_t tstep = 2 * hstep;
;     const unsigned ldsw = (unsigned)wid * 1024u;
;     const int aoff = lds_byte(wr * 64 + fr, fq * 8), boff = lds_byte(wc * 32 + fr, fq * 8);
;     ...
;         PG8_WAIT_V(2); PG8_BAR;
;         PG8_STAGE(PG8_SB(1, 0), cB + kstep, voffB); PG8_STAGE(PG8_SA(1, 0), cA + kstep, voffA); PG8_STAGE(PG8_SB(1, 1), cB + hstep + kstep, voffB);
;         PG8_WAIT_V(6); PG8_BAR;
.LBB0_819:
	s_add_u32 s16, s6, 0x17500000
	s_mov_b64 s[18:19], 0x80
	s_addc_u32 s17, s7, 0
	s_add_i32 m0, s0, 0x18000
	v_lshl_add_u64 v[10:11], v[10:11], 0, s[18:19]
	s_waitcnt vmcnt(2)
	s_barrier
	global_load_lds_dwordx4 v[10:11], off
	v_lshl_add_u64 v[6:7], v[6:7], 0, s[18:19]
	s_add_i32 m0, s0, 0x1a000
	s_add_i32 s42, s0, 0x8000
	global_load_lds_dwordx4 v[6:7], off
	v_lshl_add_u64 v[6:7], v[8:9], 0, s[18:19]
	s_mov_b32 m0, s42
	s_add_i32 s43, s0, 0xa000
	global_load_lds_dwordx4 v[6:7], off
	v_lshl_add_u64 v[6:7], v[12:13], 0, s[18:19]
	s_mov_b32 m0, s43
	v_lshl_add_u64 v[4:5], v[4:5], 0, s[18:19]
	global_load_lds_dwordx4 v[6:7], off
	s_add_i32 m0, s0, 0x1c000
	v_lshl_add_u64 v[2:3], v[2:3], 0, s[18:19]
	global_load_lds_dwordx4 v[4:5], off
	s_add_i32 m0, s0, 0x1e000
	s_lshr_b32 s5, s5, 26
	global_load_lds_dwordx4 v[2:3], off
	v_and_b32_e32 v2, 15, v0
	s_add_i32 s5, s4, s5
	v_lshlrev_b32_e32 v3, 1, v18
	v_lshlrev_b32_e32 v4, 2, v0
	s_ashr_i32 s44, s5, 6
	v_lshl_or_b32 v1, s23, 6, v2
	v_lshl_or_b32 v2, v2, 6, v3
	s_lshl_b32 s5, s23, 13
	v_and_b32_e32 v4, 32, v4
	v_bitop3_b32 v5, v2, s5, v4 bitop3:0xde
	s_lshl_b32 s5, s21, 5
	s_and_b32 s5, s5, 0x60
	v_lshlrev_b32_e32 v2, 6, v0
	s_movk_i32 s6, 0x3c0
	v_and_or_b32 v2, v2, s6, v3
	s_lshl_b32 s6, s5, 7
	v_bitop3_b32 v146, s6, v2, v4 bitop3:0xf6
	v_add_u32_e32 v2, v19, v16
	v_mul_lo_u32 v2, s4, v2
	v_lshlrev_b32_e32 v2, 1, v2
	v_add3_u32 v2, v14, v2, v15
	v_mov_b32_e32 v3, v133
	s_cmp_gt_i32 s4, 63
	v_lshl_add_u64 v[138:139], s[10:11], 0, v[2:3]
	v_add_u32_e32 v2, v17, v16
	s_sext_i32_i8 s55, s20
	s_cselect_b64 s[20:21], -1, 0
	s_add_i32 s45, s44, -2
	v_mul_lo_u32 v2, s4, v2
	s_waitcnt vmcnt(6)
	s_cmpk_lt_u32 s22, 0x100
	v_lshlrev_b32_e32 v2, 1, v2
	s_cselect_b64 s[22:23], -1, 0
	v_add3_u32 v2, v14, v2, v15
	s_add_i32 s48, 0, 0x10000
	s_add_i32 s49, 0, 0x14000
	s_ashr_i32 s46, s82, 31
	s_mov_b32 s47, s82
	v_or_b32_e32 v147, s5, v18
	v_lshl_add_u64 v[140:141], s[10:11], 0, v[2:3]
	v_mov_b64_e32 v[142:143], 0x200
	v_mov_b64_e32 v[144:145], 0x1ff
	v_add_u32_e32 v148, s48, v146
	v_add_u32_e32 v149, s49, v146
	v_add_u32_e32 v150, 0, v5
	s_barrier
	s_waitcnt vmcnt(0)
	s_bitcmp1_b32 s99, 8
	s_cbranch_scc0 .Lprio_skip_2
	s_setprio 1

; #define PG8_WAIT_V(n) asm volatile("s_waitcnt vmcnt(" #n ")" ::: "memory")
; #define PG8_BAR __builtin_amdgcn_s_barrier()
;     __device__ __forceinline__ bf16_t* u(int n) const { return (bf16_t*)(ws + WS_ARENA + (size_t)n * UNIT); }
;     __host__ __device__ bool next(int i, Unit& u) const {
;         const long L = (long)i * G + c; if (L >= nwg) return false;
;         int wgid = (int)L; { const int q = nwg / NXCD, r = nwg % NXCD, xcd = wgid % NXCD, off = wgid / NXCD; wgid = (xcd < r ? xcd * (q + 1) : r * (q + 1) + (xcd - r) * q) + off; }
; template <class Epi, class Sched, bool ALIGN_EPI = false, bool SP2 = false>
; __device__ __forceinline__ void gemm_phase(PG8_LAS unsigned char* lds, const Gemm g, const Sched& S, const Epi& E) {
;     ...
;     PG8_WAIT_V(0);
;     if constexpr (!ALIGN_EPI) { if (wr == 0) PG8_BAR; }
;     PG8_BAR;
.LBB0_1382:
	v_cndmask_b32_e64 v2, 0, 1, s[12:13]
	s_mov_b64 s[4:5], s[78:79]
	v_cmp_ne_u32_e64 s[0:1], 1, v2
	s_andn2_b64 vcc, exec, s[12:13]
	v_readfirstlane_b32 s26, v0
	s_setprio 0
	s_waitcnt vmcnt(0) lgkmcnt(0)
	s_barrier
	s_cbranch_vccnz .LBB0_1411
	s_ashr_i32 s3, s2, 31
	s_lshr_b32 s7, s3, 29
	s_add_i32 s7, s2, s7
	s_and_b32 s12, s7, -8
	s_sub_i32 s14, s2, s12
	s_cmp_gt_i32 s14, -1
	s_cbranch_scc0 .LBB0_1385
	s_lshl_b32 s18, s14, 6
	s_cbranch_execz .LBB0_1386
	s_branch .LBB0_1387

; #define PG8_WAIT_V(n) asm volatile("s_waitcnt vmcnt(" #n ")" ::: "memory")
; #define PG8_BAR __builtin_amdgcn_s_barrier()
;     __device__ __forceinline__ bf16_t* u(int n) const { return (bf16_t*)(ws + WS_ARENA + (size_t)n * UNIT); }
;     __host__ __device__ bool next(int i, Unit& u) const {
;         const long L = (long)i * G + c; if (L >= nwg) return false;
;         int wgid = (int)L; { const int q = nwg / NXCD, r = nwg % NXCD, xcd = wgid % NXCD, off = wgid / NXCD; wgid = (xcd < r ? xcd * (q + 1) : r * (q + 1) + (xcd - r) * q) + off; }
; template <class Epi, class Sched, bool ALIGN_EPI = false, bool SP2 = false>
; __device__ __forceinline__ void gemm_phase(PG8_LAS unsigned char* lds, const Gemm g, const Sched& S, const Epi& E) {
;     ...
;     PG8_WAIT_V(0);
;     if constexpr (!ALIGN_EPI) { if (wr == 0) PG8_BAR; }
;     PG8_BAR;
.LBB0_1411:
	s_mov_b64 s[18:19], s[78:79]
	s_movk_i32 s4, 0x800
	s_and_b64 vcc, exec, s[0:1]
	v_readfirstlane_b32 s24, v0
	s_setprio 0
	s_waitcnt vmcnt(0) lgkmcnt(0)
	s_barrier
	s_cbranch_vccnz .LBB0_1440
	s_ashr_i32 s3, s2, 31
	s_lshr_b32 s0, s3, 29
	s_add_i32 s5, s2, s0
	s_and_b32 s0, s5, -8
	s_sub_i32 s6, s2, s0
	s_cmp_gt_i32 s6, -1
	s_cbranch_scc0 .LBB0_1414
	s_lshl_b32 s14, s6, 6
	s_cbranch_execz .LBB0_1415
	s_branch .LBB0_1416

; #define PG8_STAGE(bufoff, gbase, voff) do { _Pragma("unroll") for (int _i = 0; _i < 2; ++_i) \
;         __builtin_amdgcn_global_load_lds((const unsigned*)((const char*)(gbase) + (voff)[_i]), (PG8_LAS unsigned*)(lds + (bufoff) + ldsw + _i * 8192), 16, 0, 0); } while (0)
; #define PG8_WAIT_V(n) asm volatile("s_waitcnt vmcnt(" #n ")" ::: "memory")
; #define PG8_BAR __builtin_amdgcn_s_barrier()
; template <class Epi, class Sched, bool ALIGN_EPI = false, bool SP2 = false>
; __device__ __forceinline__ void gemm_phase(PG8_LAS unsigned char* lds, const Gemm g, const Sched& S, const Epi& E) {
;     const int tid = threadIdx.x, wid = __builtin_amdgcn_readfirstlane(tid >> 6), lane = tid & 63, wr = wid >> 2, wc = wid & 3, fr = lane & 15, fq = lane >> 4;
;     const int K = g.K, nt = K / BK;
;     unsigned voffA[2], voffB[2];
; #pragma unroll
;     for (int i = 0; i < 2; ++i) { int R, C; stage_rc(tid * 16 + i * 8192, R, C); const int Rb = Epi::PERM ? ((R & ~31) + perm32(R & 31)) : R;
;         voffA[i] = (unsigned)(R * K + C) * 2u; voffB[i] = (unsigned)(Rb * K + C) * 2u; }
;     const size_t kstep = (size_t)(BK * 2);
;     const size_t hstep = (size_t)HALF * K * 2;
;     const size_t tstep = 2 * hstep;
;     const unsigned ldsw = (unsigned)wid * 1024u;
;     const int aoff = lds_byte(wr * 64 + fr, fq * 8), boff = lds_byte(wc * 32 + fr, fq * 8);
;     ...
;         PG8_WAIT_V(2); PG8_BAR;
;         PG8_STAGE(PG8_SB(1, 0), cB + kstep, voffB); PG8_STAGE(PG8_SA(1, 0), cA + kstep, voffA); PG8_STAGE(PG8_SB(1, 1), cB + hstep + kstep, voffB);
;         PG8_WAIT_V(6); PG8_BAR;
.LBB0_1794:
	s_add_u32 s14, s4, 0x17500000
	s_mov_b64 s[16:17], 0x80
	s_addc_u32 s15, s5, 0
	s_add_i32 m0, s35, 0x18000
	v_lshl_add_u64 v[10:11], v[10:11], 0, s[16:17]
	s_waitcnt vmcnt(2)
	s_barrier
	global_load_lds_dwordx4 v[10:11], off
	v_lshl_add_u64 v[6:7], v[6:7], 0, s[16:17]
	s_add_i32 m0, s35, 0x1a000
	s_add_i32 s40, s35, 0x8000
	global_load_lds_dwordx4 v[6:7], off
	v_lshl_add_u64 v[6:7], v[8:9], 0, s[16:17]
	s_mov_b32 m0, s40
	s_add_i32 s41, s35, 0xa000
	global_load_lds_dwordx4 v[6:7], off
	v_lshl_add_u64 v[6:7], v[12:13], 0, s[16:17]
	s_mov_b32 m0, s41
	v_lshl_add_u64 v[4:5], v[4:5], 0, s[16:17]
	global_load_lds_dwordx4 v[6:7], off
	s_add_i32 m0, s35, 0x1c000
	v_lshl_add_u64 v[2:3], v[2:3], 0, s[16:17]
	global_load_lds_dwordx4 v[4:5], off
	s_add_i32 m0, s35, 0x1e000
	s_lshr_b32 s1, s1, 26
	global_load_lds_dwordx4 v[2:3], off
	v_and_b32_e32 v2, 15, v0
	s_add_i32 s1, s0, s1
	v_lshlrev_b32_e32 v3, 1, v18
	v_lshlrev_b32_e32 v4, 2, v0
	s_ashr_i32 s42, s1, 6
	v_lshl_or_b32 v1, s21, 6, v2
	v_lshl_or_b32 v2, v2, 6, v3
	s_lshl_b32 s1, s21, 13
	v_and_b32_e32 v4, 32, v4
	v_bitop3_b32 v5, v2, s1, v4 bitop3:0xde
	s_lshl_b32 s1, s19, 5
	s_and_b32 s1, s1, 0x60
	v_lshlrev_b32_e32 v2, 6, v0
	s_movk_i32 s4, 0x3c0
	v_and_or_b32 v2, v2, s4, v3
	s_lshl_b32 s4, s1, 7
	v_bitop3_b32 v146, s4, v2, v4 bitop3:0xf6
	v_add_u32_e32 v2, v19, v16
	v_mul_lo_u32 v2, s0, v2
	v_lshlrev_b32_e32 v2, 1, v2
	v_add3_u32 v2, v14, v2, v15
	v_mov_b32_e32 v3, v133
	s_cmp_gt_i32 s0, 63
	v_lshl_add_u64 v[138:139], s[8:9], 0, v[2:3]
	v_add_u32_e32 v2, v17, v16
	s_sext_i32_i8 s53, s18
	s_cselect_b64 s[18:19], -1, 0
	s_add_i32 s43, s42, -2
	v_mul_lo_u32 v2, s0, v2
	s_waitcnt vmcnt(6)
	s_cmpk_lt_u32 s20, 0x100
	v_lshlrev_b32_e32 v2, 1, v2
	s_cselect_b64 s[20:21], -1, 0
	v_add3_u32 v2, v14, v2, v15
	s_add_i32 s46, 0, 0x10000
	s_add_i32 s47, 0, 0x14000
	s_ashr_i32 s44, s82, 31
	s_mov_b32 s45, s82
	v_or_b32_e32 v147, s1, v18
	v_lshl_add_u64 v[140:141], s[8:9], 0, v[2:3]
	v_mov_b64_e32 v[142:143], 0x200
	v_mov_b64_e32 v[144:145], 0x1ff
	v_add_u32_e32 v148, s46, v146
	v_add_u32_e32 v149, s47, v146
	v_add_u32_e32 v150, 0, v5
	s_barrier
	s_waitcnt vmcnt(0)
	s_bitcmp1_b32 s99, 8
	s_cbranch_scc0 .Lprio_skip_3
	s_setprio 1

; #define PG8_STAGE(bufoff, gbase, voff) do { _Pragma("unroll") for (int _i = 0; _i < 2; ++_i) \
;         __builtin_amdgcn_global_load_lds((const unsigned*)((const char*)(gbase) + (voff)[_i]), (PG8_LAS unsigned*)(lds + (bufoff) + ldsw + _i * 8192), 16, 0, 0); } while (0)
; #define PG8_WAIT_V(n) asm volatile("s_waitcnt vmcnt(" #n ")" ::: "memory")
; #define PG8_BAR __builtin_amdgcn_s_barrier()
; template <class Epi, class Sched, bool ALIGN_EPI = false, bool SP2 = false>
; __device__ __forceinline__ void gemm_phase(PG8_LAS unsigned char* lds, const Gemm g, const Sched& S, const Epi& E) {
;     const int tid = threadIdx.x, wid = __builtin_amdgcn_readfirstlane(tid >> 6), lane = tid & 63, wr = wid >> 2, wc = wid & 3, fr = lane & 15, fq = lane >> 4;
;     const int K = g.K, nt = K / BK;
;     unsigned voffA[2], voffB[2];
; #pragma unroll
;     for (int i = 0; i < 2; ++i) { int R, C; stage_rc(tid * 16 + i * 8192, R, C); const int Rb = Epi::PERM ? ((R & ~31) + perm32(R & 31)) : R;
;         voffA[i] = (unsigned)(R * K + C) * 2u; voffB[i] = (unsigned)(Rb * K + C) * 2u; }
;     const size_t kstep = (size_t)(BK * 2);
;     const size_t hstep = (size_t)HALF * K * 2;
;     const size_t tstep = 2 * hstep;
;     const unsigned ldsw = (unsigned)wid * 1024u;
;     const int aoff = lds_byte(wr * 64 + fr, fq * 8), boff = lds_byte(wc * 32 + fr, fq * 8);
;     ...
;         PG8_WAIT_V(2); PG8_BAR;
;         PG8_STAGE(PG8_SB(1, 0), cB + kstep, voffB); PG8_STAGE(PG8_SA(1, 0), cA + kstep, voffA); PG8_STAGE(PG8_SB(1, 1), cB + hstep + kstep, voffB);
;         PG8_WAIT_V(6); PG8_BAR;
.LBB0_1965:
	s_add_u32 s14, s4, 0xc500000
	s_mov_b64 s[16:17], 0x80
	s_addc_u32 s15, s5, 0
	s_add_i32 m0, s36, 0x18000
	v_lshl_add_u64 v[10:11], v[10:11], 0, s[16:17]
	s_waitcnt vmcnt(2)
	s_barrier
	global_load_lds_dwordx4 v[10:11], off
	v_lshl_add_u64 v[6:7], v[6:7], 0, s[16:17]
	s_add_i32 m0, s36, 0x1a000
	s_add_i32 s41, s36, 0x8000
	global_load_lds_dwordx4 v[6:7], off
	v_lshl_add_u64 v[6:7], v[8:9], 0, s[16:17]
	s_mov_b32 m0, s41
	s_add_i32 s42, s36, 0xa000
	global_load_lds_dwordx4 v[6:7], off
	v_lshl_add_u64 v[6:7], v[12:13], 0, s[16:17]
	s_mov_b32 m0, s42
	v_lshl_add_u64 v[4:5], v[4:5], 0, s[16:17]
	global_load_lds_dwordx4 v[6:7], off
	s_add_i32 m0, s36, 0x1c000
	v_lshl_add_u64 v[2:3], v[2:3], 0, s[16:17]
	global_load_lds_dwordx4 v[4:5], off
	s_add_i32 m0, s36, 0x1e000
	s_lshr_b32 s1, s1, 26
	global_load_lds_dwordx4 v[2:3], off
	v_and_b32_e32 v2, 15, v0
	s_add_i32 s1, s0, s1
	v_lshlrev_b32_e32 v3, 1, v16
	v_lshlrev_b32_e32 v4, 2, v0
	s_ashr_i32 s43, s1, 6
	v_lshl_or_b32 v1, s21, 6, v2
	v_lshl_or_b32 v2, v2, 6, v3
	s_lshl_b32 s1, s21, 13
	v_and_b32_e32 v4, 32, v4
	v_bitop3_b32 v5, v2, s1, v4 bitop3:0xde
	s_lshl_b32 s1, s19, 5
	s_and_b32 s1, s1, 0x60
	v_lshlrev_b32_e32 v2, 6, v0
	s_movk_i32 s4, 0x3c0
	v_and_or_b32 v2, v2, s4, v3
	s_lshl_b32 s4, s1, 7
	v_bitop3_b32 v146, s4, v2, v4 bitop3:0xf6
	v_add_u32_e32 v2, v18, v17
	v_mul_lo_u32 v2, s0, v2
	v_lshlrev_b32_e32 v2, 1, v2
	v_add3_u32 v2, v14, v2, v15
	v_mov_b32_e32 v3, v135
	s_cmp_gt_i32 s0, 63
	v_lshl_add_u64 v[138:139], s[8:9], 0, v[2:3]
	v_add_u32_e32 v2, v19, v17
	s_sext_i32_i16 s55, s18
	s_cselect_b64 s[18:19], -1, 0
	s_add_i32 s44, s43, -2
	v_mul_lo_u32 v2, s0, v2
	s_waitcnt vmcnt(6)
	s_cmpk_lt_u32 s20, 0x100
	v_lshlrev_b32_e32 v2, 1, v2
	s_cselect_b64 s[20:21], -1, 0
	v_add3_u32 v2, v14, v2, v15
	s_add_i32 s47, 0, 0x10000
	s_add_i32 s48, 0, 0x14000
	s_ashr_i32 s45, s82, 31
	s_mov_b32 s46, s82
	v_or_b32_e32 v147, s1, v16
	v_lshl_add_u64 v[140:141], s[8:9], 0, v[2:3]
	v_mov_b64_e32 v[142:143], 0xb00
	v_mov_b64_e32 v[144:145], 0xaff
	v_add_u32_e32 v148, s47, v146
	v_add_u32_e32 v149, s48, v146
	v_add_u32_e32 v150, 0, v5
	s_movk_i32 s49, 0x2c00
	s_barrier
	s_waitcnt vmcnt(0)
	s_bitcmp1_b32 s99, 8
	s_cbranch_scc0 .Lprio_skip_4
	s_setprio 1
